# M4: placement: K-loop MFMA runs A,B,D shifted to 4 mod 8 (all four runs now at 4 mod 8)
# baseline (speedup 1.0000x reference)
; #define PG8_STAGE(bufoff, gbase, voff) do { _Pragma("unroll") for (int _i = 0; _i < 2; ++_i) { unsigned _vo = (voff)[_i]; asm volatile("" : "+v"(_vo));   \
;         __builtin_amdgcn_global_load_lds((const unsigned*)((const char*)(gbase) + _vo), (LAS unsigned*)(lds + (bufoff) + ldsw + _i * 8192), 16, 0, 0); } } while (0)
; #define PG8_LDA(dst, b, h) do { _Pragma("unroll") for (int m = 0; m < 4; ++m) _Pragma("unroll") for (int k = 0; k < 2; ++k) dst[m][k] = *(const LAS bf16x8*)(lds + PG8_SA(b, h) + aoff + m * 2048 + k * 1024); } while (0)
; #define PG8_LDB(dst, b, h) do { _Pragma("unroll") for (int n = 0; n < 2; ++n) _Pragma("unroll") for (int k = 0; k < 2; ++k) dst[n][k] = *(const LAS bf16x8*)(lds + PG8_SB(b, h) + boff + n * 2048 + k * 1024); } while (0)
; #define PG8_MMA(ai, bj, At, Bt) do { __builtin_amdgcn_s_setprio(1); _Pragma("unroll") for (int m = 0; m < 4; ++m) _Pragma("unroll") for (int n = 0; n < 2; ++n) _Pragma("unroll") for (int k = 0; k < 2; ++k) \
;         acc[ai][bj][m][n] = __builtin_amdgcn_mfma_f32_16x16x32_bf16(Bt[n][k], At[m][k], acc[ai][bj][m][n], 0, 0, 0); __builtin_amdgcn_s_setprio(0); } while (0)
; #define PG8_WAIT_V(n) asm volatile("s_waitcnt vmcnt(" #n ")" ::: "memory")
; #define PG8_WAIT_L(n) asm volatile("s_waitcnt lgkmcnt(" #n ")" ::: "memory")
; #define PG8_BAR __builtin_amdgcn_s_barrier()
; #define PG8_SCHED __builtin_amdgcn_sched_barrier(0)
; __device__ __forceinline__ void gemm_phase(LAS unsigned char* lds, const Call& C, const int tid, const Args& args) {
;     ...
;             PG8_LDB(B0, 0, 0); PG8_LDB(B1, 0, 1); PG8_SCHED; PG8_LDA(At, 0, 0); PG8_STAGE(PG8_SA(1, 1), a1 + hstepA, voffA);
;             PG8_WAIT_V(8); PG8_WAIT_L(0); PG8_BAR; PG8_MMA(0, 0, At, B0); PG8_MMA(0, 1, At, B1); PG8_BAR; PG8_SCHED;
;             PG8_LDA(At, 0, 1); PG8_STAGE(PG8_SB(0, 0), b2, voffB); PG8_STAGE(PG8_SB(0, 1), b2 + hstepB, voffB); PG8_STAGE(PG8_SA(0, 0), a2, voffA);
;             PG8_WAIT_V(8); PG8_WAIT_L(0); PG8_BAR; PG8_MMA(1, 0, At, B0); PG8_MMA(1, 1, At, B1); PG8_BAR; PG8_SCHED;
.Lnu_nofetch:
	s_add_i32 s25, s24, 2
	s_add_u32 s8, s0, 0x100
	s_addc_u32 s9, s1, 0
	s_add_i32 s34, 0, 0x10000
	s_cmp_eq_u32 s13, s24
	s_cselect_b32 s39, s87, s9
	s_cselect_b32 s38, s86, s8
	v_add_u32_e32 v80, s34, v245
	s_cselect_b32 s41, s49, s17
	s_cselect_b32 s40, s48, s16
	s_add_i32 s24, 0, 0x14000
	ds_read_b128 v[136:139], v80
	ds_read_b128 v[140:143], v80 offset:1024
	ds_read_b128 v[144:147], v80 offset:2048
	ds_read_b128 v[148:151], v80 offset:3072
	v_add_u32_e32 v80, s24, v245
	ds_read_b128 v[152:155], v80
	ds_read_b128 v[156:159], v80 offset:1024
	ds_read_b128 v[160:163], v80 offset:2048
	ds_read_b128 v[164:167], v80 offset:3072
	v_mov_b32_e32 v80, v205
	s_add_u32 s0, s0, s89
	ds_read_b128 v[168:171], v246
	ds_read_b128 v[172:175], v246 offset:1024
	ds_read_b128 v[176:179], v246 offset:2048
	ds_read_b128 v[180:183], v246 offset:3072
	ds_read_b128 v[184:187], v246 offset:4096
	ds_read_b128 v[188:191], v246 offset:5120
	ds_read_b128 v[192:195], v246 offset:6144
	ds_read_b128 v[196:199], v246 offset:7168
	s_addc_u32 s1, s1, s94
	s_add_i32 m0, s20, 0xc000
	s_nop 0
	global_load_lds_dwordx4 v80, s[0:1]
	v_mov_b32_e32 v80, v243
	s_add_i32 m0, s20, 0xe000
	s_nop 0
	global_load_lds_dwordx4 v80, s[0:1]
	s_nop 0
	s_waitcnt vmcnt(8)
	s_waitcnt lgkmcnt(0)
	s_barrier
	s_setprio 1
	s_waitcnt lgkmcnt(0)
	v_mfma_f32_16x16x32_bf16 v[132:135], v[136:139], v[168:171], v[132:135]
	v_mfma_f32_16x16x32_bf16 v[128:131], v[144:147], v[168:171], v[128:131]
	v_mfma_f32_16x16x32_bf16 v[124:127], v[136:139], v[176:179], v[124:127]
	v_mfma_f32_16x16x32_bf16 v[120:123], v[144:147], v[176:179], v[120:123]
	v_mfma_f32_16x16x32_bf16 v[108:111], v[136:139], v[184:187], v[108:111]
	v_mfma_f32_16x16x32_bf16 v[104:107], v[144:147], v[184:187], v[104:107]
	v_mfma_f32_16x16x32_bf16 v[92:95], v[136:139], v[192:195], v[92:95]
	v_mfma_f32_16x16x32_bf16 v[86:89], v[144:147], v[192:195], v[88:91]
	v_mfma_f32_16x16x32_bf16 v[132:135], v[140:143], v[172:175], v[132:135]
	v_mfma_f32_16x16x32_bf16 v[128:131], v[148:151], v[172:175], v[128:131]
	v_mfma_f32_16x16x32_bf16 v[124:127], v[140:143], v[180:183], v[124:127]
	v_mfma_f32_16x16x32_bf16 v[120:123], v[148:151], v[180:183], v[120:123]
	v_mfma_f32_16x16x32_bf16 v[108:111], v[140:143], v[188:191], v[108:111]
	v_mfma_f32_16x16x32_bf16 v[104:107], v[148:151], v[188:191], v[104:107]
	v_mfma_f32_16x16x32_bf16 v[92:95], v[140:143], v[196:199], v[92:95]
	v_mfma_f32_16x16x32_bf16 v[86:89], v[148:151], v[196:199], v[86:89]
	s_setprio 0
	s_setprio 1
	v_mfma_f32_16x16x32_bf16 v[116:119], v[152:155], v[168:171], v[116:119]
	v_mfma_f32_16x16x32_bf16 v[112:115], v[160:163], v[168:171], v[112:115]
	v_mfma_f32_16x16x32_bf16 v[100:103], v[152:155], v[176:179], v[100:103]
	v_mfma_f32_16x16x32_bf16 v[96:99], v[160:163], v[176:179], v[96:99]
	v_mfma_f32_16x16x32_bf16 v[76:79], v[152:155], v[184:187], v[76:79]
	v_mfma_f32_16x16x32_bf16 v[72:75], v[160:163], v[184:187], v[72:75]
	v_mfma_f32_16x16x32_bf16 v[68:71], v[152:155], v[192:195], v[68:71]
	v_mfma_f32_16x16x32_bf16 v[60:63], v[160:163], v[192:195], v[60:63]
	v_mfma_f32_16x16x32_bf16 v[116:119], v[156:159], v[172:175], v[116:119]
	v_mfma_f32_16x16x32_bf16 v[112:115], v[164:167], v[172:175], v[112:115]
	v_mfma_f32_16x16x32_bf16 v[100:103], v[156:159], v[180:183], v[100:103]
	v_mfma_f32_16x16x32_bf16 v[96:99], v[164:167], v[180:183], v[96:99]
	v_mfma_f32_16x16x32_bf16 v[76:79], v[156:159], v[188:191], v[76:79]
	v_mfma_f32_16x16x32_bf16 v[72:75], v[164:167], v[188:191], v[72:75]
	v_mfma_f32_16x16x32_bf16 v[68:71], v[156:159], v[196:199], v[68:71]
	v_mfma_f32_16x16x32_bf16 v[60:63], v[164:167], v[196:199], v[60:63]
	s_setprio 0
	s_barrier
	s_nop 0
	v_mov_b32_e32 v80, v242
	s_add_i32 s0, s34, s23
	ds_read_b128 v[168:171], v246 offset:16384
	ds_read_b128 v[172:175], v246 offset:17408
	ds_read_b128 v[176:179], v246 offset:18432
	ds_read_b128 v[180:183], v246 offset:19456
	ds_read_b128 v[184:187], v246 offset:20480
	ds_read_b128 v[188:191], v246 offset:21504
	ds_read_b128 v[192:195], v246 offset:22528
	ds_read_b128 v[196:199], v246 offset:23552
	s_mov_b32 m0, s0
	s_nop 0
	global_load_lds_dwordx4 v80, s[40:41]
	v_mov_b32_e32 v80, v244
	s_add_i32 m0, s0, 0x2000
	s_add_u32 s0, s40, s74
	global_load_lds_dwordx4 v80, s[40:41]
	s_addc_u32 s1, s41, s75
	v_mov_b32_e32 v80, v242
	s_add_i32 s24, s24, s23
	s_mov_b32 m0, s24
	s_nop 0
	global_load_lds_dwordx4 v80, s[0:1]
	v_mov_b32_e32 v80, v244
	s_add_i32 m0, s24, 0x2000
	s_nop 0
	global_load_lds_dwordx4 v80, s[0:1]
	v_mov_b32_e32 v80, v205
	s_mov_b32 m0, s20
	s_nop 0
	global_load_lds_dwordx4 v80, s[38:39]
	v_mov_b32_e32 v80, v243
	s_mov_b32 m0, s72
	s_nop 0
	global_load_lds_dwordx4 v80, s[38:39]
	s_nop 0
	s_waitcnt vmcnt(8)
	s_waitcnt lgkmcnt(0)
	s_barrier
	s_setprio 1
	s_waitcnt lgkmcnt(0)
	v_mfma_f32_16x16x32_bf16 v[64:67], v[136:139], v[168:171], v[64:67]
	v_mfma_f32_16x16x32_bf16 v[56:59], v[144:147], v[168:171], v[56:59]
	v_mfma_f32_16x16x32_bf16 v[52:55], v[136:139], v[176:179], v[52:55]
	v_mfma_f32_16x16x32_bf16 v[48:51], v[144:147], v[176:179], v[48:51]
	v_mfma_f32_16x16x32_bf16 v[36:39], v[136:139], v[184:187], v[36:39]
	v_mfma_f32_16x16x32_bf16 v[32:35], v[144:147], v[184:187], v[32:35]
	v_mfma_f32_16x16x32_bf16 v[20:23], v[136:139], v[192:195], v[20:23]
	v_mfma_f32_16x16x32_bf16 v[16:19], v[144:147], v[192:195], v[16:19]
	v_mfma_f32_16x16x32_bf16 v[64:67], v[140:143], v[172:175], v[64:67]
	v_mfma_f32_16x16x32_bf16 v[56:59], v[148:151], v[172:175], v[56:59]
	v_mfma_f32_16x16x32_bf16 v[52:55], v[140:143], v[180:183], v[52:55]
	v_mfma_f32_16x16x32_bf16 v[48:51], v[148:151], v[180:183], v[48:51]
	v_mfma_f32_16x16x32_bf16 v[36:39], v[140:143], v[188:191], v[36:39]
	v_mfma_f32_16x16x32_bf16 v[32:35], v[148:151], v[188:191], v[32:35]
	v_mfma_f32_16x16x32_bf16 v[20:23], v[140:143], v[196:199], v[20:23]
	v_mfma_f32_16x16x32_bf16 v[16:19], v[148:151], v[196:199], v[16:19]
	s_setprio 0
	s_setprio 1
	v_mfma_f32_16x16x32_bf16 v[44:47], v[152:155], v[168:171], v[44:47]
	v_mfma_f32_16x16x32_bf16 v[40:43], v[160:163], v[168:171], v[40:43]
	v_mfma_f32_16x16x32_bf16 v[28:31], v[152:155], v[176:179], v[28:31]
	v_mfma_f32_16x16x32_bf16 v[24:27], v[160:163], v[176:179], v[24:27]
	v_mfma_f32_16x16x32_bf16 v[12:15], v[152:155], v[184:187], v[12:15]
	v_mfma_f32_16x16x32_bf16 v[8:11], v[160:163], v[184:187], v[8:11]
	v_mfma_f32_16x16x32_bf16 v[4:7], v[152:155], v[192:195], v[4:7]
	v_mfma_f32_16x16x32_bf16 v[0:3], v[160:163], v[192:195], v[0:3]
	v_mfma_f32_16x16x32_bf16 v[44:47], v[156:159], v[172:175], v[44:47]
	v_mfma_f32_16x16x32_bf16 v[40:43], v[164:167], v[172:175], v[40:43]
	v_mfma_f32_16x16x32_bf16 v[28:31], v[156:159], v[180:183], v[28:31]
	v_mfma_f32_16x16x32_bf16 v[24:27], v[164:167], v[180:183], v[24:27]
	v_mfma_f32_16x16x32_bf16 v[12:15], v[156:159], v[188:191], v[12:15]
	v_mfma_f32_16x16x32_bf16 v[8:11], v[164:167], v[188:191], v[8:11]
	v_mfma_f32_16x16x32_bf16 v[4:7], v[156:159], v[196:199], v[4:7]
	v_mfma_f32_16x16x32_bf16 v[0:3], v[164:167], v[196:199], v[0:3]
	s_setprio 0
	s_barrier
	s_nop 0
; #define PG8_STAGE(bufoff, gbase, voff) do { _Pragma("unroll") for (int _i = 0; _i < 2; ++_i) { unsigned _vo = (voff)[_i]; asm volatile("" : "+v"(_vo));   \
;         __builtin_amdgcn_global_load_lds((const unsigned*)((const char*)(gbase) + _vo), (LAS unsigned*)(lds + (bufoff) + ldsw + _i * 8192), 16, 0, 0); } } while (0)
; #define PG8_LDA(dst, b, h) do { _Pragma("unroll") for (int m = 0; m < 4; ++m) _Pragma("unroll") for (int k = 0; k < 2; ++k) dst[m][k] = *(const LAS bf16x8*)(lds + PG8_SA(b, h) + aoff + m * 2048 + k * 1024); } while (0)
; #define PG8_LDB(dst, b, h) do { _Pragma("unroll") for (int n = 0; n < 2; ++n) _Pragma("unroll") for (int k = 0; k < 2; ++k) dst[n][k] = *(const LAS bf16x8*)(lds + PG8_SB(b, h) + boff + n * 2048 + k * 1024); } while (0)
; #define PG8_MMA(ai, bj, At, Bt) do { __builtin_amdgcn_s_setprio(1); _Pragma("unroll") for (int m = 0; m < 4; ++m) _Pragma("unroll") for (int n = 0; n < 2; ++n) _Pragma("unroll") for (int k = 0; k < 2; ++k) \
;         acc[ai][bj][m][n] = __builtin_amdgcn_mfma_f32_16x16x32_bf16(Bt[n][k], At[m][k], acc[ai][bj][m][n], 0, 0, 0); __builtin_amdgcn_s_setprio(0); } while (0)
; #define PG8_WAIT_V(n) asm volatile("s_waitcnt vmcnt(" #n ")" ::: "memory")
; #define PG8_WAIT_L(n) asm volatile("s_waitcnt lgkmcnt(" #n ")" ::: "memory")
; #define PG8_BAR __builtin_amdgcn_s_barrier()
; #define PG8_SCHED __builtin_amdgcn_sched_barrier(0)
; __device__ __forceinline__ void gemm_phase(LAS unsigned char* lds, const Call& C, const int tid, const Args& args) {
;     ...
;             PG8_LDB(B0, 1, 0); PG8_LDB(B1, 1, 1); PG8_SCHED; PG8_LDA(At, 1, 0); PG8_STAGE(PG8_SA(0, 1), a2 + hstepA, voffA);
;             PG8_WAIT_V(8); PG8_WAIT_L(0); PG8_BAR; PG8_MMA(0, 0, At, B0); PG8_MMA(0, 1, At, B1); PG8_BAR; PG8_SCHED;
.Lp7_ph3:
	s_add_i32 s24, 0, 0x18000
	v_add_u32_e32 v80, s24, v245
	s_add_i32 s42, 0, 0x1c000
	ds_read_b128 v[136:139], v80
	ds_read_b128 v[140:143], v80 offset:1024
	ds_read_b128 v[144:147], v80 offset:2048
	ds_read_b128 v[148:151], v80 offset:3072
	v_add_u32_e32 v80, s42, v245
	ds_read_b128 v[152:155], v80
	ds_read_b128 v[156:159], v80 offset:1024
	ds_read_b128 v[160:163], v80 offset:2048
	ds_read_b128 v[164:167], v80 offset:3072
	s_add_u32 s34, s38, s22
	v_mov_b32_e32 v80, v205
	s_mov_b32 m0, s73
	ds_read_b128 v[168:171], v246 offset:32768
	ds_read_b128 v[172:175], v246 offset:33792
	ds_read_b128 v[176:179], v246 offset:34816
	ds_read_b128 v[180:183], v246 offset:35840
	ds_read_b128 v[184:187], v246 offset:36864
	ds_read_b128 v[188:191], v246 offset:37888
	ds_read_b128 v[192:195], v246 offset:38912
	ds_read_b128 v[196:199], v246 offset:39936
	s_addc_u32 s35, s39, 0
	s_nop 0
	global_load_lds_dwordx4 v80, s[34:35]
	v_mov_b32_e32 v80, v243
	s_mov_b32 m0, s4
	s_nop 0
	global_load_lds_dwordx4 v80, s[34:35]
	s_waitcnt vmcnt(8)
	s_waitcnt lgkmcnt(0)
	s_barrier
	s_setprio 1
	s_waitcnt lgkmcnt(0)
	v_mfma_f32_16x16x32_bf16 v[132:135], v[136:139], v[168:171], v[132:135]
	v_mfma_f32_16x16x32_bf16 v[128:131], v[144:147], v[168:171], v[128:131]
	v_mfma_f32_16x16x32_bf16 v[124:127], v[136:139], v[176:179], v[124:127]
	v_mfma_f32_16x16x32_bf16 v[120:123], v[144:147], v[176:179], v[120:123]
	v_mfma_f32_16x16x32_bf16 v[108:111], v[136:139], v[184:187], v[108:111]
	v_mfma_f32_16x16x32_bf16 v[104:107], v[144:147], v[184:187], v[104:107]
	v_mfma_f32_16x16x32_bf16 v[90:93], v[136:139], v[192:195], v[92:95]
	v_mfma_f32_16x16x32_bf16 v[86:89], v[144:147], v[192:195], v[86:89]
	v_mfma_f32_16x16x32_bf16 v[132:135], v[140:143], v[172:175], v[132:135]
	v_mfma_f32_16x16x32_bf16 v[128:131], v[148:151], v[172:175], v[128:131]
	v_mfma_f32_16x16x32_bf16 v[124:127], v[140:143], v[180:183], v[124:127]
	v_mfma_f32_16x16x32_bf16 v[120:123], v[148:151], v[180:183], v[120:123]
	v_mfma_f32_16x16x32_bf16 v[108:111], v[140:143], v[188:191], v[108:111]
	v_mfma_f32_16x16x32_bf16 v[104:107], v[148:151], v[188:191], v[104:107]
	v_mfma_f32_16x16x32_bf16 v[92:95], v[140:143], v[196:199], v[90:93]
	v_mfma_f32_16x16x32_bf16 v[88:91], v[148:151], v[196:199], v[86:89]
	s_setprio 0
	s_setprio 1
	v_mfma_f32_16x16x32_bf16 v[116:119], v[152:155], v[168:171], v[116:119]
	v_mfma_f32_16x16x32_bf16 v[112:115], v[160:163], v[168:171], v[112:115]
	v_mfma_f32_16x16x32_bf16 v[100:103], v[152:155], v[176:179], v[100:103]
	v_mfma_f32_16x16x32_bf16 v[96:99], v[160:163], v[176:179], v[96:99]
	v_mfma_f32_16x16x32_bf16 v[76:79], v[152:155], v[184:187], v[76:79]
	v_mfma_f32_16x16x32_bf16 v[72:75], v[160:163], v[184:187], v[72:75]
	v_mfma_f32_16x16x32_bf16 v[68:71], v[152:155], v[192:195], v[68:71]
	v_mfma_f32_16x16x32_bf16 v[60:63], v[160:163], v[192:195], v[60:63]
	v_mfma_f32_16x16x32_bf16 v[116:119], v[156:159], v[172:175], v[116:119]
	v_mfma_f32_16x16x32_bf16 v[112:115], v[164:167], v[172:175], v[112:115]
	v_mfma_f32_16x16x32_bf16 v[100:103], v[156:159], v[180:183], v[100:103]
	v_mfma_f32_16x16x32_bf16 v[96:99], v[164:167], v[180:183], v[96:99]
	v_mfma_f32_16x16x32_bf16 v[76:79], v[156:159], v[188:191], v[76:79]
	v_mfma_f32_16x16x32_bf16 v[72:75], v[164:167], v[188:191], v[72:75]
	v_mfma_f32_16x16x32_bf16 v[68:71], v[156:159], v[196:199], v[68:71]
	v_mfma_f32_16x16x32_bf16 v[60:63], v[164:167], v[196:199], v[60:63]
	s_setprio 0
	s_barrier
; #define PG8_STAGE(bufoff, gbase, voff) do { _Pragma("unroll") for (int _i = 0; _i < 2; ++_i) { unsigned _vo = (voff)[_i]; asm volatile("" : "+v"(_vo));   \
;         __builtin_amdgcn_global_load_lds((const unsigned*)((const char*)(gbase) + _vo), (LAS unsigned*)(lds + (bufoff) + ldsw + _i * 8192), 16, 0, 0); } } while (0)
; #define PG8_LDA(dst, b, h) do { _Pragma("unroll") for (int m = 0; m < 4; ++m) _Pragma("unroll") for (int k = 0; k < 2; ++k) dst[m][k] = *(const LAS bf16x8*)(lds + PG8_SA(b, h) + aoff + m * 2048 + k * 1024); } while (0)
; #define PG8_MMA(ai, bj, At, Bt) do { __builtin_amdgcn_s_setprio(1); _Pragma("unroll") for (int m = 0; m < 4; ++m) _Pragma("unroll") for (int n = 0; n < 2; ++n) _Pragma("unroll") for (int k = 0; k < 2; ++k) \
;         acc[ai][bj][m][n] = __builtin_amdgcn_mfma_f32_16x16x32_bf16(Bt[n][k], At[m][k], acc[ai][bj][m][n], 0, 0, 0); __builtin_amdgcn_s_setprio(0); } while (0)
; #define PG8_WAIT_V(n) asm volatile("s_waitcnt vmcnt(" #n ")" ::: "memory")
; #define PG8_WAIT_L(n) asm volatile("s_waitcnt lgkmcnt(" #n ")" ::: "memory")
; #define PG8_BAR __builtin_amdgcn_s_barrier()
; #define PG8_SCHED __builtin_amdgcn_sched_barrier(0)
; __device__ __forceinline__ void gemm_phase(LAS unsigned char* lds, const Call& C, const int tid, const Args& args) {
;     ...
;             PG8_LDA(At, 1, 1); PG8_STAGE(PG8_SB(1, 0), b3, voffB); PG8_STAGE(PG8_SB(1, 1), b3 + hstepB, voffB); PG8_STAGE(PG8_SA(1, 0), a3, voffA);
;             PG8_WAIT_V(8); PG8_WAIT_L(0); PG8_BAR; PG8_MMA(1, 0, At, B0); PG8_MMA(1, 1, At, B1); PG8_BAR; PG8_SCHED;
;         }
	v_mov_b32_e32 v80, v242
	ds_read_b128 v[168:171], v246 offset:49152
	ds_read_b128 v[172:175], v246 offset:50176
	ds_read_b128 v[176:179], v246 offset:51200
	ds_read_b128 v[180:183], v246 offset:52224
	ds_read_b128 v[184:187], v246 offset:53248
	ds_read_b128 v[188:191], v246 offset:54272
	ds_read_b128 v[192:195], v246 offset:55296
	ds_read_b128 v[196:199], v246 offset:56320
	s_add_i32 s24, s24, s23
	v_lshl_add_u64 v[82:83], s[40:41], 0, v[80:81]
	v_lshl_add_u64 v[82:83], v[82:83], 0, s[18:19]
	s_mov_b32 m0, s24
	v_mov_b32_e32 v80, v244
	global_load_lds_dwordx4 v[82:83], off
	s_add_i32 m0, s24, 0x2000
	v_lshl_add_u64 v[82:83], s[40:41], 0, v[80:81]
	v_lshl_add_u64 v[82:83], v[82:83], 0, s[18:19]
	v_mov_b32_e32 v80, v242
	global_load_lds_dwordx4 v[82:83], off
	s_add_i32 s24, s42, s23
	v_lshl_add_u64 v[82:83], s[0:1], 0, v[80:81]
	v_lshl_add_u64 v[82:83], v[82:83], 0, s[18:19]
	s_mov_b32 m0, s24
	v_mov_b32_e32 v80, v244
	global_load_lds_dwordx4 v[82:83], off
	s_add_i32 m0, s24, 0x2000
	v_lshl_add_u64 v[82:83], s[0:1], 0, v[80:81]
	v_lshl_add_u64 v[82:83], v[82:83], 0, s[18:19]
	v_mov_b32_e32 v80, v205
	global_load_lds_dwordx4 v[82:83], off
	s_mov_b32 m0, s14
	v_lshl_add_u64 v[82:83], s[38:39], 0, v[80:81]
	v_lshl_add_u64 v[82:83], v[82:83], 0, s[18:19]
	v_mov_b32_e32 v80, v243
	global_load_lds_dwordx4 v[82:83], off
	s_mov_b32 m0, s52
	v_lshl_add_u64 v[82:83], s[38:39], 0, v[80:81]
	v_lshl_add_u64 v[82:83], v[82:83], 0, s[18:19]
	global_load_lds_dwordx4 v[82:83], off
	s_nop 0
	s_waitcnt vmcnt(8)
	s_waitcnt lgkmcnt(0)
	s_barrier
	s_setprio 1
	s_waitcnt lgkmcnt(0)
	v_mfma_f32_16x16x32_bf16 v[64:67], v[136:139], v[168:171], v[64:67]
	v_mfma_f32_16x16x32_bf16 v[56:59], v[144:147], v[168:171], v[56:59]
	v_mfma_f32_16x16x32_bf16 v[52:55], v[136:139], v[176:179], v[52:55]
	v_mfma_f32_16x16x32_bf16 v[48:51], v[144:147], v[176:179], v[48:51]
	v_mfma_f32_16x16x32_bf16 v[36:39], v[136:139], v[184:187], v[36:39]
	v_mfma_f32_16x16x32_bf16 v[32:35], v[144:147], v[184:187], v[32:35]
	v_mfma_f32_16x16x32_bf16 v[20:23], v[136:139], v[192:195], v[20:23]
	v_mfma_f32_16x16x32_bf16 v[16:19], v[144:147], v[192:195], v[16:19]
	v_mfma_f32_16x16x32_bf16 v[64:67], v[140:143], v[172:175], v[64:67]
	v_mfma_f32_16x16x32_bf16 v[56:59], v[148:151], v[172:175], v[56:59]
	v_mfma_f32_16x16x32_bf16 v[52:55], v[140:143], v[180:183], v[52:55]
	v_mfma_f32_16x16x32_bf16 v[48:51], v[148:151], v[180:183], v[48:51]
	v_mfma_f32_16x16x32_bf16 v[36:39], v[140:143], v[188:191], v[36:39]
	v_mfma_f32_16x16x32_bf16 v[32:35], v[148:151], v[188:191], v[32:35]
	v_mfma_f32_16x16x32_bf16 v[20:23], v[140:143], v[196:199], v[20:23]
	v_mfma_f32_16x16x32_bf16 v[16:19], v[148:151], v[196:199], v[16:19]
	s_setprio 0
	s_setprio 1
	v_mfma_f32_16x16x32_bf16 v[44:47], v[152:155], v[168:171], v[44:47]
	v_mfma_f32_16x16x32_bf16 v[40:43], v[160:163], v[168:171], v[40:43]
	v_mfma_f32_16x16x32_bf16 v[28:31], v[152:155], v[176:179], v[28:31]
	v_mfma_f32_16x16x32_bf16 v[24:27], v[160:163], v[176:179], v[24:27]
	v_mfma_f32_16x16x32_bf16 v[12:15], v[152:155], v[184:187], v[12:15]
	v_mfma_f32_16x16x32_bf16 v[8:11], v[160:163], v[184:187], v[8:11]
	v_mfma_f32_16x16x32_bf16 v[4:7], v[152:155], v[192:195], v[4:7]
	v_mfma_f32_16x16x32_bf16 v[0:3], v[160:163], v[192:195], v[0:3]
	v_mfma_f32_16x16x32_bf16 v[44:47], v[156:159], v[172:175], v[44:47]
	v_mfma_f32_16x16x32_bf16 v[40:43], v[164:167], v[172:175], v[40:43]
	v_mfma_f32_16x16x32_bf16 v[28:31], v[156:159], v[180:183], v[28:31]
	v_mfma_f32_16x16x32_bf16 v[24:27], v[164:167], v[180:183], v[24:27]
	v_mfma_f32_16x16x32_bf16 v[12:15], v[156:159], v[188:191], v[12:15]
	v_mfma_f32_16x16x32_bf16 v[8:11], v[164:167], v[188:191], v[8:11]
	v_mfma_f32_16x16x32_bf16 v[4:7], v[156:159], v[196:199], v[4:7]
	v_mfma_f32_16x16x32_bf16 v[0:3], v[164:167], v[196:199], v[0:3]
	s_setprio 0
	s_barrier
	s_nop 0
	s_add_u32 s16, s16, 0x100
	s_addc_u32 s17, s17, 0
	s_cmp_ge_u32 s25, s12
	s_mov_b64 s[0:1], s[8:9]
	s_mov_b32 s24, s25
	s_cbranch_scc0 .LBB0_282
	s_and_b64 vcc, exec, s[80:81]
	s_cbranch_vccz .LBB0_285
